# GLA scan output tile computed transposed (MFMA operands swapped), bf16 pairs + v_permlane32_swap, 2 dwordx4 row stores per lane instead of 16 short stores
# speedup vs baseline: 1.0061x; 1.0032x over previous
.LBB0_470:
	s_or_b64 exec, exec, s[4:5]
	s_lshr_b32 s86, s77, 2
	s_lshr_b32 s87, s77, 3
	s_and_b64 s[4:5], s[48:49], exec
	s_cselect_b32 s84, s68, 0x36c00000
	s_cselect_b32 s4, 0xc0, s67
	s_add_u32 s84, s94, s84
	s_addc_u32 s85, s95, 0
	s_lshl_b32 s10, s10, 1
	s_add_u32 s10, s84, s10
	s_addc_u32 s85, s85, 0
	s_mov_b32 s5, s11
	s_add_u32 s84, s10, s53
	s_addc_u32 s85, s85, 0
	s_or_b64 s[4:5], s[4:5], s[46:47]
	v_lshl_add_u64 v[10:11], s[4:5], 0, v[10:11]
	v_lshlrev_b64 v[10:11], 11, v[10:11]
	v_lshl_add_u64 v[10:11], v[146:147], 0, v[10:11]
	global_load_dwordx4 v[140:143], v[10:11], off
	v_lshlrev_b32_e32 v12, 5, v9
	v_and_b32_e32 v19, 32, v12
	v_and_b32_e32 v17, 31, v20
	v_lshlrev_b32_e32 v12, 1, v19
	v_mov_b32_e32 v13, v145
	v_lshl_add_u64 v[12:13], s[84:85], 0, v[12:13]
	v_lshlrev_b32_e32 v14, 1, v17
	v_mov_b32_e32 v15, v145
	v_lshl_add_u64 v[150:151], v[12:13], 0, v[14:15]
	v_mul_lo_u32 v12, v0, s69
	v_mul_lo_u32 v13, v21, s74
	v_ashrrev_i32_e32 v18, 7, v20
	v_add_u32_e32 v12, 0, v12
	v_add3_u32 v203, 0, v13, v8
	v_lshlrev_b32_e32 v8, 7, v0
	v_lshlrev_b32_e32 v16, 3, v23
	v_sub_u32_e32 v8, v12, v8
	v_lshlrev_b32_e32 v11, 5, v18
	v_lshl_add_u32 v202, v144, 1, v12
	v_lshl_add_u32 v204, v16, 1, v8
	v_lshrrev_b32_e32 v8, 5, v22
	v_and_b32_e32 v12, 32, v11
	v_lshlrev_b32_e32 v15, 3, v8
	v_lshlrev_b32_e32 v16, 4, v8
	v_lshl_or_b32 v8, v8, 2, v12
	v_mad_i32_i24 v154, v8, s52, s52
	v_add_u32_e32 v156, s52, v154
	v_add_u32_e32 v158, s52, v156
	v_mad_i32_i24 v160, s52, 5, v158
	v_add_u32_e32 v162, s52, v160
	v_add_u32_e32 v164, s52, v162
	v_add_u32_e32 v166, s52, v164
	v_mad_i32_i24 v168, s52, 5, v166
	s_and_b32 s10, s86, 1
	s_and_b32 s84, s87, 3
	v_add_u32_e32 v170, s52, v168
	s_lshl_b32 s53, s10, 5
	s_lshl_b32 s10, s10, 15
	s_lshl_b32 s85, s84, 8
	v_add_u32_e32 v172, s52, v170
	v_or_b32_e32 v13, v12, v17
	v_add_u32_e32 v174, s52, v172
	s_add_u32 s50, s53, s50
	v_mul_u32_u24_e32 v14, 0x110, v13
	v_mad_i32_i24 v176, s52, 5, v174
	s_addc_u32 s51, 0, s51
	v_add3_u32 v206, 0, v14, v16
	v_or_b32_e32 v14, v19, v17
	v_add_u32_e32 v178, s52, v176
	s_add_u32 s50, s50, s84
	v_mad_u32_u24 v19, v14, s69, 0
	v_lshlrev_b32_e32 v13, 7, v13
	v_add_u32_e32 v180, s52, v178
	s_addc_u32 s51, s51, 0
	v_add_u32_e32 v207, v19, v16
	v_sub_u32_e32 v209, v206, v13
	v_lshlrev_b32_e32 v13, 7, v14
	v_mul_i32_i24_e32 v152, s52, v8
	v_add_u32_e32 v182, s52, v180
	s_lshl_b64 s[52:53], s[50:51], 19
	v_cmp_gt_i32_e64 s[4:5], 4, v9
	v_sub_u32_e32 v210, v207, v13
	v_mul_lo_u32 v13, v9, s76
	v_mov_b32_e32 v9, s53
	v_or_b32_e32 v8, s52, v144
	v_lshl_add_u64 v[184:185], v[6:7], 1, v[8:9]
	s_lshl_b64 s[52:53], s[50:51], 20
	v_and_b32_e32 v6, 3, v20
	v_lshl_or_b32 v6, v6, 5, s52
	s_add_u32 s52, s10, s46
	v_or_b32_e32 v11, v11, v17
	v_mov_b32_e32 v7, s53
	s_addc_u32 s53, 0, s47
	s_lshl_b64 s[50:51], s[50:51], 15
	s_waitcnt lgkmcnt(0)
	s_barrier
	v_and_b32_e32 v12, 0xffffff80, v20
	v_mul_lo_u32 v11, v11, s74
	v_lshl_add_u64 v[0:1], s[52:53], 0, v[0:1]
	s_add_u32 s10, s50, 0x3ec00c00
	v_lshl_add_u32 v10, v22, 1, 0
	v_add_u32_e32 v12, s75, v12
	v_add3_u32 v211, 0, v11, v16
	v_lshl_add_u32 v11, v18, 6, v19
	v_lshlrev_b64 v[188:189], 10, v[0:1]
	s_addc_u32 s50, s51, 0
	v_mov_b32_e32 v0, 0
	v_lshl_add_u32 v205, v20, 2, s75
	v_ashrrev_i32_e32 v153, 31, v152
	v_ashrrev_i32_e32 v155, 31, v154
	v_ashrrev_i32_e32 v157, 31, v156
	v_ashrrev_i32_e32 v159, 31, v158
	v_ashrrev_i32_e32 v161, 31, v160
	v_ashrrev_i32_e32 v163, 31, v162
	v_ashrrev_i32_e32 v165, 31, v164
	v_ashrrev_i32_e32 v167, 31, v166
	v_ashrrev_i32_e32 v169, 31, v168
	v_ashrrev_i32_e32 v171, 31, v170
	v_ashrrev_i32_e32 v173, 31, v172
	v_ashrrev_i32_e32 v175, 31, v174
	v_ashrrev_i32_e32 v177, 31, v176
	v_ashrrev_i32_e32 v179, 31, v178
	v_ashrrev_i32_e32 v181, 31, v180
	v_ashrrev_i32_e32 v183, 31, v182
	v_and_b32_e32 v236, 31, v208
	v_bfe_u32 v237, v208, 5, 1
	v_lshlrev_b32_e32 v226, 2, v237
	v_sub_u32_e32 v226, v236, v226
	v_sub_u32_e32 v227, v154, v152
	v_mul_lo_u32 v226, v226, v227
	v_add_u32_e32 v226, v152, v226
	v_ashrrev_i32_e32 v227, 31, v226
	v_lshlrev_b64 v[226:227], 11, v[226:227]
	v_lshl_add_u64 v[226:227], v[150:151], 0, v[226:227]
	v_lshlrev_b32_e32 v228, 4, v237
	v_lshlrev_b32_e32 v229, 1, v236
	v_sub_u32_e32 v228, v228, v229
	v_ashrrev_i32_e32 v229, 31, v228
	v_lshl_add_u64 v[152:153], v[226:227], 0, v[228:229]
	v_lshl_add_u64 v[186:187], v[4:5], 1, v[6:7]
	v_or3_b32 v188, v188, s85, v2
	v_lshl_or_b32 v190, v3, 2, s10
	v_mov_b32_e32 v191, s50
	s_mov_b32 s84, -4
	s_movk_i32 s85, 0x1c0
	s_movk_i32 s86, 0xe3f
	v_add_u32_e32 v144, v10, v13
	v_add_u32_e32 v212, v12, v16
	v_add_u32_e32 v213, v11, v15
	v_mov_b32_e32 v1, v0
	v_mov_b32_e32 v2, v0
	v_mov_b32_e32 v3, v0
	v_mov_b32_e32 v4, v0
	v_mov_b32_e32 v5, v0
	v_mov_b32_e32 v6, v0
	v_mov_b32_e32 v7, v0
	v_mov_b32_e32 v8, v0
	v_mov_b32_e32 v9, v0
	v_mov_b32_e32 v10, v0
	v_mov_b32_e32 v11, v0
	v_mov_b32_e32 v12, v0
	v_mov_b32_e32 v13, v0
	v_mov_b32_e32 v14, v0
	v_mov_b32_e32 v15, v0
	s_branch .LBB0_473

.LBB0_473:
	s_waitcnt vmcnt(22)
	ds_write_b128 v202, v[52:55] offset:17408
	ds_write_b128 v202, v[48:51] offset:17424
	s_waitcnt vmcnt(20)
	ds_write_b128 v203, v[60:63] offset:34816
	ds_write_b128 v203, v[56:59] offset:34832
	s_waitcnt vmcnt(19)
	ds_write_b128 v204, v[64:67] offset:53248
	s_waitcnt vmcnt(18)
	ds_write_b16 v144, v96 offset:62464
	ds_write_b16_d16_hi v144, v96 offset:62608
	ds_write_b16 v144, v97 offset:62752
	ds_write_b16_d16_hi v144, v97 offset:62896
	ds_write_b16 v144, v98 offset:63040
	ds_write_b16_d16_hi v144, v98 offset:63184
	ds_write_b16 v144, v99 offset:63328
	ds_write_b16_d16_hi v144, v99 offset:63472
	s_and_saveexec_b64 s[50:51], s[0:1]
	ds_write_b32 v205, v199
	s_or_b64 exec, exec, s[50:51]
	s_waitcnt lgkmcnt(0)
	s_barrier
	s_and_saveexec_b64 s[50:51], s[4:5]
	s_cbranch_execz .LBB0_477
	s_add_i32 s10, s85, 0xfffffe40
	s_add_i32 s87, s86, 0x1c0
	s_and_b64 s[52:53], s[48:49], exec
	s_cselect_b32 s10, s10, s87
	s_add_u32 s52, s46, s10
	s_addc_u32 s53, 0, s47
	s_lshl_b64 s[98:99], s[52:53], 11
	ds_read_b128 v[214:217], v209 offset:53248
	ds_read_b128 v[218:221], v210 offset:62464
	ds_read_b128 v[222:225], v209 offset:53280
	ds_read_b128 v[226:229], v210 offset:62496
	ds_read_b128 v[240:243], v209 offset:53312
	ds_read_b128 v[244:247], v210 offset:62528
	ds_read_b128 v[248:251], v209 offset:53344
	ds_read_b128 v[252:255], v210 offset:62560
	s_waitcnt lgkmcnt(6)
	v_mfma_f32_32x32x16_bf16 v[16:31], v[218:221], v[214:217], 0
	ds_read_b128 v[214:217], v206 offset:17408
	ds_read_b128 v[218:221], v207
	s_waitcnt lgkmcnt(6)
	v_mfma_f32_32x32x16_bf16 v[16:31], v[226:229], v[222:225], v[16:31]
	ds_read_b128 v[222:225], v206 offset:17440
	ds_read_b128 v[226:229], v207 offset:32
	s_waitcnt lgkmcnt(6)
	v_mfma_f32_32x32x16_bf16 v[16:31], v[244:247], v[240:243], v[16:31]
	ds_read_b128 v[240:243], v206 offset:17472
	ds_read_b128 v[244:247], v207 offset:64
	s_waitcnt lgkmcnt(6)
	v_mfma_f32_32x32x16_bf16 v[16:31], v[252:255], v[248:251], v[16:31]
	ds_read_b128 v[248:251], v206 offset:17504
	ds_read_b128 v[252:255], v207 offset:96
	s_waitcnt lgkmcnt(6)
	v_mfma_f32_32x32x16_bf16 v[32:47], v[218:221], v[214:217], 0
	ds_read_b128 v[214:217], v206 offset:17536
	ds_read_b128 v[218:221], v207 offset:128
	s_waitcnt lgkmcnt(6)
	v_mfma_f32_32x32x16_bf16 v[32:47], v[226:229], v[222:225], v[32:47]
	ds_read_b128 v[222:225], v206 offset:17568
	ds_read_b128 v[226:229], v207 offset:160
	s_waitcnt lgkmcnt(6)
	v_mfma_f32_32x32x16_bf16 v[32:47], v[244:247], v[240:243], v[32:47]
	ds_read_b128 v[240:243], v206 offset:17600
	ds_read_b128 v[244:247], v207 offset:192
	s_waitcnt lgkmcnt(6)
	v_mfma_f32_32x32x16_bf16 v[32:47], v[252:255], v[248:251], v[32:47]
	ds_read_b128 v[248:251], v206 offset:17632
	ds_read_b128 v[252:255], v207 offset:224
	s_waitcnt lgkmcnt(6)
	v_mfma_f32_32x32x16_bf16 v[32:47], v[218:221], v[214:217], v[32:47]
	s_waitcnt lgkmcnt(4)
	v_mfma_f32_32x32x16_bf16 v[32:47], v[226:229], v[222:225], v[32:47]
	s_waitcnt lgkmcnt(2)
	v_mfma_f32_32x32x16_bf16 v[32:47], v[244:247], v[240:243], v[32:47]
	s_waitcnt lgkmcnt(0)
	v_mfma_f32_32x32x16_bf16 v[32:47], v[252:255], v[248:251], v[32:47]
	s_nop 11
	v_add_f32_e32 v16, v16, v32
	v_add_f32_e32 v17, v17, v33
	v_add_f32_e32 v18, v18, v34
	v_add_f32_e32 v19, v19, v35
	v_add_f32_e32 v20, v20, v36
	v_add_f32_e32 v21, v21, v37
	v_add_f32_e32 v22, v22, v38
	v_add_f32_e32 v23, v23, v39
	v_add_f32_e32 v24, v24, v40
	v_add_f32_e32 v25, v25, v41
	v_add_f32_e32 v26, v26, v42
	v_add_f32_e32 v27, v27, v43
	v_add_f32_e32 v28, v28, v44
	v_add_f32_e32 v29, v29, v45
	v_add_f32_e32 v30, v30, v46
	v_add_f32_e32 v31, v31, v47
	v_cvt_pk_bf16_f32 v240, v16, v17
	v_cvt_pk_bf16_f32 v241, v18, v19
	v_cvt_pk_bf16_f32 v242, v20, v21
	v_cvt_pk_bf16_f32 v243, v22, v23
	v_cvt_pk_bf16_f32 v244, v24, v25
	v_cvt_pk_bf16_f32 v245, v26, v27
	v_cvt_pk_bf16_f32 v246, v28, v29
	v_cvt_pk_bf16_f32 v247, v30, v31
	v_lshl_add_u64 v[226:227], s[98:99], 0, v[152:153]
	s_nop 0
	v_permlane32_swap_b32_e32 v240, v242
	v_permlane32_swap_b32_e32 v241, v243
	v_permlane32_swap_b32_e32 v244, v246
	v_permlane32_swap_b32_e32 v245, v247
	global_store_dwordx4 v[226:227], v[240:243], off
	global_store_dwordx4 v[226:227], v[244:247], off offset:32

.Lsw0_join:
	ds_write_b16 v144, v120 offset:62464
	ds_write_b16_d16_hi v144, v120 offset:62608
	ds_write_b16 v144, v121 offset:62752
	ds_write_b16_d16_hi v144, v121 offset:62896
	ds_write_b16 v144, v122 offset:63040
	ds_write_b16_d16_hi v144, v122 offset:63184
	ds_write_b16 v144, v123 offset:63328
	ds_write_b16_d16_hi v144, v123 offset:63472
	s_and_saveexec_b64 s[52:53], s[0:1]
	ds_write_b32 v205, v198
	s_or_b64 exec, exec, s[52:53]
	s_waitcnt lgkmcnt(0)
	s_barrier
	s_and_saveexec_b64 s[52:53], s[4:5]
	s_cbranch_execz .LBB0_485
	s_add_i32 s10, s85, 0xfffffe80
	s_add_i32 s87, s86, 0x180
	s_and_b64 s[96:97], s[48:49], exec
	s_cselect_b32 s10, s10, s87
	s_add_u32 s96, s46, s10
	s_addc_u32 s97, 0, s47
	s_lshl_b64 s[98:99], s[96:97], 11
	ds_read_b128 v[214:217], v209 offset:53248
	ds_read_b128 v[218:221], v210 offset:62464
	ds_read_b128 v[222:225], v209 offset:53280
	ds_read_b128 v[226:229], v210 offset:62496
	ds_read_b128 v[240:243], v209 offset:53312
	ds_read_b128 v[244:247], v210 offset:62528
	ds_read_b128 v[248:251], v209 offset:53344
	ds_read_b128 v[252:255], v210 offset:62560
	s_waitcnt lgkmcnt(6)
	v_mfma_f32_32x32x16_bf16 v[16:31], v[218:221], v[214:217], 0
	ds_read_b128 v[214:217], v206 offset:17408
	ds_read_b128 v[218:221], v207
	s_waitcnt lgkmcnt(6)
	v_mfma_f32_32x32x16_bf16 v[16:31], v[226:229], v[222:225], v[16:31]
	ds_read_b128 v[222:225], v206 offset:17440
	ds_read_b128 v[226:229], v207 offset:32
	s_waitcnt lgkmcnt(6)
	v_mfma_f32_32x32x16_bf16 v[16:31], v[244:247], v[240:243], v[16:31]
	ds_read_b128 v[240:243], v206 offset:17472
	ds_read_b128 v[244:247], v207 offset:64
	s_waitcnt lgkmcnt(6)
	v_mfma_f32_32x32x16_bf16 v[16:31], v[252:255], v[248:251], v[16:31]
	ds_read_b128 v[248:251], v206 offset:17504
	ds_read_b128 v[252:255], v207 offset:96
	s_waitcnt lgkmcnt(6)
	v_mfma_f32_32x32x16_bf16 v[32:47], v[218:221], v[214:217], 0
	ds_read_b128 v[214:217], v206 offset:17536
	ds_read_b128 v[218:221], v207 offset:128
	s_waitcnt lgkmcnt(6)
	v_mfma_f32_32x32x16_bf16 v[32:47], v[226:229], v[222:225], v[32:47]
	ds_read_b128 v[222:225], v206 offset:17568
	ds_read_b128 v[226:229], v207 offset:160
	s_waitcnt lgkmcnt(6)
	v_mfma_f32_32x32x16_bf16 v[32:47], v[244:247], v[240:243], v[32:47]
	ds_read_b128 v[240:243], v206 offset:17600
	ds_read_b128 v[244:247], v207 offset:192
	s_waitcnt lgkmcnt(6)
	v_mfma_f32_32x32x16_bf16 v[32:47], v[252:255], v[248:251], v[32:47]
	ds_read_b128 v[248:251], v206 offset:17632
	ds_read_b128 v[252:255], v207 offset:224
	s_waitcnt lgkmcnt(6)
	v_mfma_f32_32x32x16_bf16 v[32:47], v[218:221], v[214:217], v[32:47]
	s_waitcnt lgkmcnt(4)
	v_mfma_f32_32x32x16_bf16 v[32:47], v[226:229], v[222:225], v[32:47]
	s_waitcnt lgkmcnt(2)
	v_mfma_f32_32x32x16_bf16 v[32:47], v[244:247], v[240:243], v[32:47]
	s_waitcnt lgkmcnt(0)
	v_mfma_f32_32x32x16_bf16 v[32:47], v[252:255], v[248:251], v[32:47]
	s_nop 11
	v_add_f32_e32 v16, v16, v32
	v_add_f32_e32 v17, v17, v33
	v_add_f32_e32 v18, v18, v34
	v_add_f32_e32 v19, v19, v35
	v_add_f32_e32 v20, v20, v36
	v_add_f32_e32 v21, v21, v37
	v_add_f32_e32 v22, v22, v38
	v_add_f32_e32 v23, v23, v39
	v_add_f32_e32 v24, v24, v40
	v_add_f32_e32 v25, v25, v41
	v_add_f32_e32 v26, v26, v42
	v_add_f32_e32 v27, v27, v43
	v_add_f32_e32 v28, v28, v44
	v_add_f32_e32 v29, v29, v45
	v_add_f32_e32 v30, v30, v46
	v_add_f32_e32 v31, v31, v47
	v_cvt_pk_bf16_f32 v240, v16, v17
	v_cvt_pk_bf16_f32 v241, v18, v19
	v_cvt_pk_bf16_f32 v242, v20, v21
	v_cvt_pk_bf16_f32 v243, v22, v23
	v_cvt_pk_bf16_f32 v244, v24, v25
	v_cvt_pk_bf16_f32 v245, v26, v27
	v_cvt_pk_bf16_f32 v246, v28, v29
	v_cvt_pk_bf16_f32 v247, v30, v31
	v_lshl_add_u64 v[226:227], s[98:99], 0, v[152:153]
	s_nop 0
	v_permlane32_swap_b32_e32 v240, v242
	v_permlane32_swap_b32_e32 v241, v243
	v_permlane32_swap_b32_e32 v244, v246
	v_permlane32_swap_b32_e32 v245, v247
	global_store_dwordx4 v[226:227], v[240:243], off
	global_store_dwordx4 v[226:227], v[244:247], off offset:32

.Lsw1_join:
	ds_write_b16 v144, v136 offset:62464
	ds_write_b16_d16_hi v144, v136 offset:62608
	ds_write_b16 v144, v137 offset:62752
	ds_write_b16_d16_hi v144, v137 offset:62896
	ds_write_b16 v144, v138 offset:63040
	ds_write_b16_d16_hi v144, v138 offset:63184
	ds_write_b16 v144, v139 offset:63328
	ds_write_b16_d16_hi v144, v139 offset:63472
	s_and_saveexec_b64 s[52:53], s[0:1]
	ds_write_b32 v205, v201
	s_or_b64 exec, exec, s[52:53]
	s_waitcnt lgkmcnt(0)
	s_barrier
	s_and_saveexec_b64 s[52:53], s[4:5]
	s_cbranch_execz .LBB0_493
	s_add_i32 s10, s85, 0xfffffec0
	s_add_i32 s87, s86, 0x140
	s_and_b64 s[96:97], s[48:49], exec
	s_cselect_b32 s10, s10, s87
	s_add_u32 s96, s46, s10
	s_addc_u32 s97, 0, s47
	s_lshl_b64 s[98:99], s[96:97], 11
	ds_read_b128 v[214:217], v209 offset:53248
	ds_read_b128 v[218:221], v210 offset:62464
	ds_read_b128 v[222:225], v209 offset:53280
	ds_read_b128 v[226:229], v210 offset:62496
	ds_read_b128 v[240:243], v209 offset:53312
	ds_read_b128 v[244:247], v210 offset:62528
	ds_read_b128 v[248:251], v209 offset:53344
	ds_read_b128 v[252:255], v210 offset:62560
	s_waitcnt lgkmcnt(6)
	v_mfma_f32_32x32x16_bf16 v[16:31], v[218:221], v[214:217], 0
	ds_read_b128 v[214:217], v206 offset:17408
	ds_read_b128 v[218:221], v207
	s_waitcnt lgkmcnt(6)
	v_mfma_f32_32x32x16_bf16 v[16:31], v[226:229], v[222:225], v[16:31]
	ds_read_b128 v[222:225], v206 offset:17440
	ds_read_b128 v[226:229], v207 offset:32
	s_waitcnt lgkmcnt(6)
	v_mfma_f32_32x32x16_bf16 v[16:31], v[244:247], v[240:243], v[16:31]
	ds_read_b128 v[240:243], v206 offset:17472
	ds_read_b128 v[244:247], v207 offset:64
	s_waitcnt lgkmcnt(6)
	v_mfma_f32_32x32x16_bf16 v[16:31], v[252:255], v[248:251], v[16:31]
	ds_read_b128 v[248:251], v206 offset:17504
	ds_read_b128 v[252:255], v207 offset:96
	s_waitcnt lgkmcnt(6)
	v_mfma_f32_32x32x16_bf16 v[32:47], v[218:221], v[214:217], 0
	ds_read_b128 v[214:217], v206 offset:17536
	ds_read_b128 v[218:221], v207 offset:128
	s_waitcnt lgkmcnt(6)
	v_mfma_f32_32x32x16_bf16 v[32:47], v[226:229], v[222:225], v[32:47]
	ds_read_b128 v[222:225], v206 offset:17568
	ds_read_b128 v[226:229], v207 offset:160
	s_waitcnt lgkmcnt(6)
	v_mfma_f32_32x32x16_bf16 v[32:47], v[244:247], v[240:243], v[32:47]
	ds_read_b128 v[240:243], v206 offset:17600
	ds_read_b128 v[244:247], v207 offset:192
	s_waitcnt lgkmcnt(6)
	v_mfma_f32_32x32x16_bf16 v[32:47], v[252:255], v[248:251], v[32:47]
	ds_read_b128 v[248:251], v206 offset:17632
	ds_read_b128 v[252:255], v207 offset:224
	s_waitcnt lgkmcnt(6)
	v_mfma_f32_32x32x16_bf16 v[32:47], v[218:221], v[214:217], v[32:47]
	s_waitcnt lgkmcnt(4)
	v_mfma_f32_32x32x16_bf16 v[32:47], v[226:229], v[222:225], v[32:47]
	s_waitcnt lgkmcnt(2)
	v_mfma_f32_32x32x16_bf16 v[32:47], v[244:247], v[240:243], v[32:47]
	s_waitcnt lgkmcnt(0)
	v_mfma_f32_32x32x16_bf16 v[32:47], v[252:255], v[248:251], v[32:47]
	s_nop 11
	v_add_f32_e32 v16, v16, v32
	v_add_f32_e32 v17, v17, v33
	v_add_f32_e32 v18, v18, v34
	v_add_f32_e32 v19, v19, v35
	v_add_f32_e32 v20, v20, v36
	v_add_f32_e32 v21, v21, v37
	v_add_f32_e32 v22, v22, v38
	v_add_f32_e32 v23, v23, v39
	v_add_f32_e32 v24, v24, v40
	v_add_f32_e32 v25, v25, v41
	v_add_f32_e32 v26, v26, v42
	v_add_f32_e32 v27, v27, v43
	v_add_f32_e32 v28, v28, v44
	v_add_f32_e32 v29, v29, v45
	v_add_f32_e32 v30, v30, v46
	v_add_f32_e32 v31, v31, v47
	v_cvt_pk_bf16_f32 v240, v16, v17
	v_cvt_pk_bf16_f32 v241, v18, v19
	v_cvt_pk_bf16_f32 v242, v20, v21
	v_cvt_pk_bf16_f32 v243, v22, v23
	v_cvt_pk_bf16_f32 v244, v24, v25
	v_cvt_pk_bf16_f32 v245, v26, v27
	v_cvt_pk_bf16_f32 v246, v28, v29
	v_cvt_pk_bf16_f32 v247, v30, v31
	v_lshl_add_u64 v[226:227], s[98:99], 0, v[152:153]
	s_nop 0
	v_permlane32_swap_b32_e32 v240, v242
	v_permlane32_swap_b32_e32 v241, v243
	v_permlane32_swap_b32_e32 v244, v246
	v_permlane32_swap_b32_e32 v245, v247
	global_store_dwordx4 v[226:227], v[240:243], off
	global_store_dwordx4 v[226:227], v[244:247], off offset:32

.Lsw2_join:
	ds_write_b16 v144, v140 offset:62464
	ds_write_b16_d16_hi v144, v140 offset:62608
	ds_write_b16 v144, v141 offset:62752
	ds_write_b16_d16_hi v144, v141 offset:62896
	ds_write_b16 v144, v142 offset:63040
	ds_write_b16_d16_hi v144, v142 offset:63184
	ds_write_b16 v144, v143 offset:63328
	ds_write_b16_d16_hi v144, v143 offset:63472
	s_and_saveexec_b64 s[52:53], s[0:1]
	ds_write_b32 v205, v200
	s_or_b64 exec, exec, s[52:53]
	s_waitcnt lgkmcnt(0)
	s_barrier
	s_and_saveexec_b64 s[52:53], s[4:5]
	s_cbranch_execz .LBB0_501
	s_add_i32 s10, s85, 0xffffff00
	s_add_i32 s87, s86, 0x100
	s_and_b64 s[96:97], s[48:49], exec
	s_cselect_b32 s10, s10, s87
	s_add_u32 s96, s46, s10
	s_addc_u32 s97, 0, s47
	s_lshl_b64 s[98:99], s[96:97], 11
	ds_read_b128 v[214:217], v209 offset:53248
	ds_read_b128 v[218:221], v210 offset:62464
	ds_read_b128 v[222:225], v209 offset:53280
	ds_read_b128 v[226:229], v210 offset:62496
	ds_read_b128 v[240:243], v209 offset:53312
	ds_read_b128 v[244:247], v210 offset:62528
	ds_read_b128 v[248:251], v209 offset:53344
	ds_read_b128 v[252:255], v210 offset:62560
	s_waitcnt lgkmcnt(6)
	v_mfma_f32_32x32x16_bf16 v[16:31], v[218:221], v[214:217], 0
	ds_read_b128 v[214:217], v206 offset:17408
	ds_read_b128 v[218:221], v207
	s_waitcnt lgkmcnt(6)
	v_mfma_f32_32x32x16_bf16 v[16:31], v[226:229], v[222:225], v[16:31]
	ds_read_b128 v[222:225], v206 offset:17440
	ds_read_b128 v[226:229], v207 offset:32
	s_waitcnt lgkmcnt(6)
	v_mfma_f32_32x32x16_bf16 v[16:31], v[244:247], v[240:243], v[16:31]
	ds_read_b128 v[240:243], v206 offset:17472
	ds_read_b128 v[244:247], v207 offset:64
	s_waitcnt lgkmcnt(6)
	v_mfma_f32_32x32x16_bf16 v[16:31], v[252:255], v[248:251], v[16:31]
	ds_read_b128 v[248:251], v206 offset:17504
	ds_read_b128 v[252:255], v207 offset:96
	s_waitcnt lgkmcnt(6)
	v_mfma_f32_32x32x16_bf16 v[32:47], v[218:221], v[214:217], 0
	ds_read_b128 v[214:217], v206 offset:17536
	ds_read_b128 v[218:221], v207 offset:128
	s_waitcnt lgkmcnt(6)
	v_mfma_f32_32x32x16_bf16 v[32:47], v[226:229], v[222:225], v[32:47]
	ds_read_b128 v[222:225], v206 offset:17568
	ds_read_b128 v[226:229], v207 offset:160
	s_waitcnt lgkmcnt(6)
	v_mfma_f32_32x32x16_bf16 v[32:47], v[244:247], v[240:243], v[32:47]
	ds_read_b128 v[240:243], v206 offset:17600
	ds_read_b128 v[244:247], v207 offset:192
	s_waitcnt lgkmcnt(6)
	v_mfma_f32_32x32x16_bf16 v[32:47], v[252:255], v[248:251], v[32:47]
	ds_read_b128 v[248:251], v206 offset:17632
	ds_read_b128 v[252:255], v207 offset:224
	s_waitcnt lgkmcnt(6)
	v_mfma_f32_32x32x16_bf16 v[32:47], v[218:221], v[214:217], v[32:47]
	s_waitcnt lgkmcnt(4)
	v_mfma_f32_32x32x16_bf16 v[32:47], v[226:229], v[222:225], v[32:47]
	s_waitcnt lgkmcnt(2)
	v_mfma_f32_32x32x16_bf16 v[32:47], v[244:247], v[240:243], v[32:47]
	s_waitcnt lgkmcnt(0)
	v_mfma_f32_32x32x16_bf16 v[32:47], v[252:255], v[248:251], v[32:47]
	s_nop 11
	v_add_f32_e32 v16, v16, v32
	v_add_f32_e32 v17, v17, v33
	v_add_f32_e32 v18, v18, v34
	v_add_f32_e32 v19, v19, v35
	v_add_f32_e32 v20, v20, v36
	v_add_f32_e32 v21, v21, v37
	v_add_f32_e32 v22, v22, v38
	v_add_f32_e32 v23, v23, v39
	v_add_f32_e32 v24, v24, v40
	v_add_f32_e32 v25, v25, v41
	v_add_f32_e32 v26, v26, v42
	v_add_f32_e32 v27, v27, v43
	v_add_f32_e32 v28, v28, v44
	v_add_f32_e32 v29, v29, v45
	v_add_f32_e32 v30, v30, v46
	v_add_f32_e32 v31, v31, v47
	v_cvt_pk_bf16_f32 v240, v16, v17
	v_cvt_pk_bf16_f32 v241, v18, v19
	v_cvt_pk_bf16_f32 v242, v20, v21
	v_cvt_pk_bf16_f32 v243, v22, v23
	v_cvt_pk_bf16_f32 v244, v24, v25
	v_cvt_pk_bf16_f32 v245, v26, v27
	v_cvt_pk_bf16_f32 v246, v28, v29
	v_cvt_pk_bf16_f32 v247, v30, v31
	v_lshl_add_u64 v[226:227], s[98:99], 0, v[152:153]
	s_nop 0
	v_permlane32_swap_b32_e32 v240, v242
	v_permlane32_swap_b32_e32 v241, v243
	v_permlane32_swap_b32_e32 v244, v246
	v_permlane32_swap_b32_e32 v245, v247
	global_store_dwordx4 v[226:227], v[240:243], off
	global_store_dwordx4 v[226:227], v[244:247], off offset:32

.LBB0_863:
	s_or_b64 exec, exec, s[4:5]
	s_lshr_b32 s80, s77, 2
	s_lshr_b32 s81, s77, 3
	s_and_b64 s[4:5], s[48:49], exec
	s_cselect_b32 s78, s68, 0x36c00000
	s_cselect_b32 s4, 0xc0, s67
	s_add_u32 s78, s94, s78
	s_addc_u32 s79, s95, 0
	s_lshl_b32 s10, s10, 1
	s_add_u32 s10, s78, s10
	s_addc_u32 s79, s79, 0
	s_mov_b32 s5, s11
	s_add_u32 s78, s10, s53
	s_addc_u32 s79, s79, 0
	s_or_b64 s[4:5], s[4:5], s[46:47]
	v_lshl_add_u64 v[10:11], s[4:5], 0, v[10:11]
	v_lshlrev_b64 v[10:11], 11, v[10:11]
	v_lshl_add_u64 v[10:11], v[146:147], 0, v[10:11]
	global_load_dwordx4 v[140:143], v[10:11], off
	v_lshlrev_b32_e32 v12, 5, v9
	v_and_b32_e32 v19, 32, v12
	v_and_b32_e32 v17, 31, v20
	v_lshlrev_b32_e32 v12, 1, v19
	v_mov_b32_e32 v13, v145
	v_lshl_add_u64 v[12:13], s[78:79], 0, v[12:13]
	v_lshlrev_b32_e32 v14, 1, v17
	v_mov_b32_e32 v15, v145
	v_lshl_add_u64 v[150:151], v[12:13], 0, v[14:15]
	v_mul_lo_u32 v12, v0, s69
	v_mul_lo_u32 v13, v21, s74
	v_ashrrev_i32_e32 v18, 7, v20
	v_add_u32_e32 v12, 0, v12
	v_add3_u32 v203, 0, v13, v8
	v_lshlrev_b32_e32 v8, 7, v0
	v_lshlrev_b32_e32 v16, 3, v23
	v_sub_u32_e32 v8, v12, v8
	v_lshlrev_b32_e32 v11, 5, v18
	v_lshl_add_u32 v202, v144, 1, v12
	v_lshl_add_u32 v204, v16, 1, v8
	v_lshrrev_b32_e32 v8, 5, v22
	v_and_b32_e32 v12, 32, v11
	v_lshlrev_b32_e32 v15, 3, v8
	v_lshlrev_b32_e32 v16, 4, v8
	v_lshl_or_b32 v8, v8, 2, v12
	v_mad_i32_i24 v154, v8, s52, s52
	v_add_u32_e32 v156, s52, v154
	v_add_u32_e32 v158, s52, v156
	v_mad_i32_i24 v160, s52, 5, v158
	v_add_u32_e32 v162, s52, v160
	v_add_u32_e32 v164, s52, v162
	v_add_u32_e32 v166, s52, v164
	v_mad_i32_i24 v168, s52, 5, v166
	s_and_b32 s10, s80, 1
	s_and_b32 s78, s81, 3
	v_add_u32_e32 v170, s52, v168
	s_lshl_b32 s53, s10, 5
	s_lshl_b32 s10, s10, 15
	s_lshl_b32 s79, s78, 8
	v_add_u32_e32 v172, s52, v170
	v_or_b32_e32 v13, v12, v17
	v_add_u32_e32 v174, s52, v172
	s_add_u32 s50, s53, s50
	v_mul_u32_u24_e32 v14, 0x110, v13
	v_mad_i32_i24 v176, s52, 5, v174
	s_addc_u32 s51, 0, s51
	v_add3_u32 v206, 0, v14, v16
	v_or_b32_e32 v14, v19, v17
	v_add_u32_e32 v178, s52, v176
	s_add_u32 s50, s50, s78
	v_mad_u32_u24 v19, v14, s69, 0
	v_lshlrev_b32_e32 v13, 7, v13
	v_add_u32_e32 v180, s52, v178
	s_addc_u32 s51, s51, 0
	v_add_u32_e32 v207, v19, v16
	v_sub_u32_e32 v209, v206, v13
	v_lshlrev_b32_e32 v13, 7, v14
	v_mul_i32_i24_e32 v152, s52, v8
	v_add_u32_e32 v182, s52, v180
	s_lshl_b64 s[52:53], s[50:51], 19
	v_cmp_gt_i32_e64 s[4:5], 4, v9
	v_sub_u32_e32 v210, v207, v13
	v_mul_lo_u32 v13, v9, s76
	v_mov_b32_e32 v9, s53
	v_or_b32_e32 v8, s52, v144
	v_lshl_add_u64 v[184:185], v[6:7], 1, v[8:9]
	s_lshl_b64 s[52:53], s[50:51], 20
	v_and_b32_e32 v6, 3, v20
	v_lshl_or_b32 v6, v6, 5, s52
	s_add_u32 s52, s10, s46
	v_or_b32_e32 v11, v11, v17
	v_mov_b32_e32 v7, s53
	s_addc_u32 s53, 0, s47
	s_lshl_b64 s[50:51], s[50:51], 15
	s_waitcnt lgkmcnt(0)
	s_barrier
	v_and_b32_e32 v12, 0xffffff80, v20
	v_mul_lo_u32 v11, v11, s74
	v_lshl_add_u64 v[0:1], s[52:53], 0, v[0:1]
	s_add_u32 s10, s50, 0x3ec00c00
	v_lshl_add_u32 v10, v22, 1, 0
	v_add_u32_e32 v12, s75, v12
	v_add3_u32 v211, 0, v11, v16
	v_lshl_add_u32 v11, v18, 6, v19
	v_lshlrev_b64 v[188:189], 10, v[0:1]
	s_addc_u32 s50, s51, 0
	v_mov_b32_e32 v0, 0
	v_lshl_add_u32 v205, v20, 2, s75
	v_ashrrev_i32_e32 v153, 31, v152
	v_ashrrev_i32_e32 v155, 31, v154
	v_ashrrev_i32_e32 v157, 31, v156
	v_ashrrev_i32_e32 v159, 31, v158
	v_ashrrev_i32_e32 v161, 31, v160
	v_ashrrev_i32_e32 v163, 31, v162
	v_ashrrev_i32_e32 v165, 31, v164
	v_ashrrev_i32_e32 v167, 31, v166
	v_ashrrev_i32_e32 v169, 31, v168
	v_ashrrev_i32_e32 v171, 31, v170
	v_ashrrev_i32_e32 v173, 31, v172
	v_ashrrev_i32_e32 v175, 31, v174
	v_ashrrev_i32_e32 v177, 31, v176
	v_ashrrev_i32_e32 v179, 31, v178
	v_ashrrev_i32_e32 v181, 31, v180
	v_ashrrev_i32_e32 v183, 31, v182
	v_and_b32_e32 v236, 31, v208
	v_bfe_u32 v237, v208, 5, 1
	v_lshlrev_b32_e32 v226, 2, v237
	v_sub_u32_e32 v226, v236, v226
	v_sub_u32_e32 v227, v154, v152
	v_mul_lo_u32 v226, v226, v227
	v_add_u32_e32 v226, v152, v226
	v_ashrrev_i32_e32 v227, 31, v226
	v_lshlrev_b64 v[226:227], 11, v[226:227]
	v_lshl_add_u64 v[226:227], v[150:151], 0, v[226:227]
	v_lshlrev_b32_e32 v228, 4, v237
	v_lshlrev_b32_e32 v229, 1, v236
	v_sub_u32_e32 v228, v228, v229
	v_ashrrev_i32_e32 v229, 31, v228
	v_lshl_add_u64 v[152:153], v[226:227], 0, v[228:229]
	v_lshl_add_u64 v[186:187], v[4:5], 1, v[6:7]
	v_or3_b32 v188, v188, s79, v2
	v_lshl_or_b32 v190, v3, 2, s10
	v_mov_b32_e32 v191, s50
	s_mov_b32 s78, -4
	s_movk_i32 s79, 0x1c0
	s_movk_i32 s80, 0xe3f
	v_add_u32_e32 v144, v10, v13
	v_add_u32_e32 v212, v12, v16
	v_add_u32_e32 v213, v11, v15
	v_mov_b32_e32 v1, v0
	v_mov_b32_e32 v2, v0
	v_mov_b32_e32 v3, v0
	v_mov_b32_e32 v4, v0
	v_mov_b32_e32 v5, v0
	v_mov_b32_e32 v6, v0
	v_mov_b32_e32 v7, v0
	v_mov_b32_e32 v8, v0
	v_mov_b32_e32 v9, v0
	v_mov_b32_e32 v10, v0
	v_mov_b32_e32 v11, v0
	v_mov_b32_e32 v12, v0
	v_mov_b32_e32 v13, v0
	v_mov_b32_e32 v14, v0
	v_mov_b32_e32 v15, v0
	s_branch .LBB0_866

.LBB0_866:
	s_waitcnt vmcnt(22)
	ds_write_b128 v202, v[52:55] offset:17408
	ds_write_b128 v202, v[48:51] offset:17424
	s_waitcnt vmcnt(20)
	ds_write_b128 v203, v[60:63] offset:34816
	ds_write_b128 v203, v[56:59] offset:34832
	s_waitcnt vmcnt(19)
	ds_write_b128 v204, v[64:67] offset:53248
	s_waitcnt vmcnt(18)
	ds_write_b16 v144, v96 offset:62464
	ds_write_b16_d16_hi v144, v96 offset:62608
	ds_write_b16 v144, v97 offset:62752
	ds_write_b16_d16_hi v144, v97 offset:62896
	ds_write_b16 v144, v98 offset:63040
	ds_write_b16_d16_hi v144, v98 offset:63184
	ds_write_b16 v144, v99 offset:63328
	ds_write_b16_d16_hi v144, v99 offset:63472
	s_and_saveexec_b64 s[50:51], s[0:1]
	ds_write_b32 v205, v199
	s_or_b64 exec, exec, s[50:51]
	s_waitcnt lgkmcnt(0)
	s_barrier
	s_and_saveexec_b64 s[50:51], s[4:5]
	s_cbranch_execz .LBB0_870
	s_add_i32 s10, s79, 0xfffffe40
	s_add_i32 s81, s80, 0x1c0
	s_and_b64 s[52:53], s[48:49], exec
	s_cselect_b32 s10, s10, s81
	s_add_u32 s52, s46, s10
	s_addc_u32 s53, 0, s47
	s_lshl_b64 s[98:99], s[52:53], 11
	ds_read_b128 v[214:217], v209 offset:53248
	ds_read_b128 v[218:221], v210 offset:62464
	ds_read_b128 v[222:225], v209 offset:53280
	ds_read_b128 v[226:229], v210 offset:62496
	ds_read_b128 v[240:243], v209 offset:53312
	ds_read_b128 v[244:247], v210 offset:62528
	ds_read_b128 v[248:251], v209 offset:53344
	ds_read_b128 v[252:255], v210 offset:62560
	s_waitcnt lgkmcnt(6)
	v_mfma_f32_32x32x16_bf16 v[16:31], v[218:221], v[214:217], 0
	ds_read_b128 v[214:217], v206 offset:17408
	ds_read_b128 v[218:221], v207
	s_waitcnt lgkmcnt(6)
	v_mfma_f32_32x32x16_bf16 v[16:31], v[226:229], v[222:225], v[16:31]
	ds_read_b128 v[222:225], v206 offset:17440
	ds_read_b128 v[226:229], v207 offset:32
	s_waitcnt lgkmcnt(6)
	v_mfma_f32_32x32x16_bf16 v[16:31], v[244:247], v[240:243], v[16:31]
	ds_read_b128 v[240:243], v206 offset:17472
	ds_read_b128 v[244:247], v207 offset:64
	s_waitcnt lgkmcnt(6)
	v_mfma_f32_32x32x16_bf16 v[16:31], v[252:255], v[248:251], v[16:31]
	ds_read_b128 v[248:251], v206 offset:17504
	ds_read_b128 v[252:255], v207 offset:96
	s_waitcnt lgkmcnt(6)
	v_mfma_f32_32x32x16_bf16 v[32:47], v[218:221], v[214:217], 0
	ds_read_b128 v[214:217], v206 offset:17536
	ds_read_b128 v[218:221], v207 offset:128
	s_waitcnt lgkmcnt(6)
	v_mfma_f32_32x32x16_bf16 v[32:47], v[226:229], v[222:225], v[32:47]
	ds_read_b128 v[222:225], v206 offset:17568
	ds_read_b128 v[226:229], v207 offset:160
	s_waitcnt lgkmcnt(6)
	v_mfma_f32_32x32x16_bf16 v[32:47], v[244:247], v[240:243], v[32:47]
	ds_read_b128 v[240:243], v206 offset:17600
	ds_read_b128 v[244:247], v207 offset:192
	s_waitcnt lgkmcnt(6)
	v_mfma_f32_32x32x16_bf16 v[32:47], v[252:255], v[248:251], v[32:47]
	ds_read_b128 v[248:251], v206 offset:17632
	ds_read_b128 v[252:255], v207 offset:224
	s_waitcnt lgkmcnt(6)
	v_mfma_f32_32x32x16_bf16 v[32:47], v[218:221], v[214:217], v[32:47]
	s_waitcnt lgkmcnt(4)
	v_mfma_f32_32x32x16_bf16 v[32:47], v[226:229], v[222:225], v[32:47]
	s_waitcnt lgkmcnt(2)
	v_mfma_f32_32x32x16_bf16 v[32:47], v[244:247], v[240:243], v[32:47]
	s_waitcnt lgkmcnt(0)
	v_mfma_f32_32x32x16_bf16 v[32:47], v[252:255], v[248:251], v[32:47]
	s_nop 11
	v_add_f32_e32 v16, v16, v32
	v_add_f32_e32 v17, v17, v33
	v_add_f32_e32 v18, v18, v34
	v_add_f32_e32 v19, v19, v35
	v_add_f32_e32 v20, v20, v36
	v_add_f32_e32 v21, v21, v37
	v_add_f32_e32 v22, v22, v38
	v_add_f32_e32 v23, v23, v39
	v_add_f32_e32 v24, v24, v40
	v_add_f32_e32 v25, v25, v41
	v_add_f32_e32 v26, v26, v42
	v_add_f32_e32 v27, v27, v43
	v_add_f32_e32 v28, v28, v44
	v_add_f32_e32 v29, v29, v45
	v_add_f32_e32 v30, v30, v46
	v_add_f32_e32 v31, v31, v47
	v_cvt_pk_bf16_f32 v240, v16, v17
	v_cvt_pk_bf16_f32 v241, v18, v19
	v_cvt_pk_bf16_f32 v242, v20, v21
	v_cvt_pk_bf16_f32 v243, v22, v23
	v_cvt_pk_bf16_f32 v244, v24, v25
	v_cvt_pk_bf16_f32 v245, v26, v27
	v_cvt_pk_bf16_f32 v246, v28, v29
	v_cvt_pk_bf16_f32 v247, v30, v31
	v_lshl_add_u64 v[226:227], s[98:99], 0, v[152:153]
	s_nop 0
	v_permlane32_swap_b32_e32 v240, v242
	v_permlane32_swap_b32_e32 v241, v243
	v_permlane32_swap_b32_e32 v244, v246
	v_permlane32_swap_b32_e32 v245, v247
	global_store_dwordx4 v[226:227], v[240:243], off
	global_store_dwordx4 v[226:227], v[244:247], off offset:32

.Lsw3_join:
	ds_write_b16 v144, v120 offset:62464
	ds_write_b16_d16_hi v144, v120 offset:62608
	ds_write_b16 v144, v121 offset:62752
	ds_write_b16_d16_hi v144, v121 offset:62896
	ds_write_b16 v144, v122 offset:63040
	ds_write_b16_d16_hi v144, v122 offset:63184
	ds_write_b16 v144, v123 offset:63328
	ds_write_b16_d16_hi v144, v123 offset:63472
	s_and_saveexec_b64 s[52:53], s[0:1]
	ds_write_b32 v205, v198
	s_or_b64 exec, exec, s[52:53]
	s_waitcnt lgkmcnt(0)
	s_barrier
	s_and_saveexec_b64 s[52:53], s[4:5]
	s_cbranch_execz .LBB0_878
	s_add_i32 s10, s79, 0xfffffe80
	s_add_i32 s81, s80, 0x180
	s_and_b64 s[84:85], s[48:49], exec
	s_cselect_b32 s10, s10, s81
	s_add_u32 s84, s46, s10
	s_addc_u32 s85, 0, s47
	s_lshl_b64 s[98:99], s[84:85], 11
	ds_read_b128 v[214:217], v209 offset:53248
	ds_read_b128 v[218:221], v210 offset:62464
	ds_read_b128 v[222:225], v209 offset:53280
	ds_read_b128 v[226:229], v210 offset:62496
	ds_read_b128 v[240:243], v209 offset:53312
	ds_read_b128 v[244:247], v210 offset:62528
	ds_read_b128 v[248:251], v209 offset:53344
	ds_read_b128 v[252:255], v210 offset:62560
	s_waitcnt lgkmcnt(6)
	v_mfma_f32_32x32x16_bf16 v[16:31], v[218:221], v[214:217], 0
	ds_read_b128 v[214:217], v206 offset:17408
	ds_read_b128 v[218:221], v207
	s_waitcnt lgkmcnt(6)
	v_mfma_f32_32x32x16_bf16 v[16:31], v[226:229], v[222:225], v[16:31]
	ds_read_b128 v[222:225], v206 offset:17440
	ds_read_b128 v[226:229], v207 offset:32
	s_waitcnt lgkmcnt(6)
	v_mfma_f32_32x32x16_bf16 v[16:31], v[244:247], v[240:243], v[16:31]
	ds_read_b128 v[240:243], v206 offset:17472
	ds_read_b128 v[244:247], v207 offset:64
	s_waitcnt lgkmcnt(6)
	v_mfma_f32_32x32x16_bf16 v[16:31], v[252:255], v[248:251], v[16:31]
	ds_read_b128 v[248:251], v206 offset:17504
	ds_read_b128 v[252:255], v207 offset:96
	s_waitcnt lgkmcnt(6)
	v_mfma_f32_32x32x16_bf16 v[32:47], v[218:221], v[214:217], 0
	ds_read_b128 v[214:217], v206 offset:17536
	ds_read_b128 v[218:221], v207 offset:128
	s_waitcnt lgkmcnt(6)
	v_mfma_f32_32x32x16_bf16 v[32:47], v[226:229], v[222:225], v[32:47]
	ds_read_b128 v[222:225], v206 offset:17568
	ds_read_b128 v[226:229], v207 offset:160
	s_waitcnt lgkmcnt(6)
	v_mfma_f32_32x32x16_bf16 v[32:47], v[244:247], v[240:243], v[32:47]
	ds_read_b128 v[240:243], v206 offset:17600
	ds_read_b128 v[244:247], v207 offset:192
	s_waitcnt lgkmcnt(6)
	v_mfma_f32_32x32x16_bf16 v[32:47], v[252:255], v[248:251], v[32:47]
	ds_read_b128 v[248:251], v206 offset:17632
	ds_read_b128 v[252:255], v207 offset:224
	s_waitcnt lgkmcnt(6)
	v_mfma_f32_32x32x16_bf16 v[32:47], v[218:221], v[214:217], v[32:47]
	s_waitcnt lgkmcnt(4)
	v_mfma_f32_32x32x16_bf16 v[32:47], v[226:229], v[222:225], v[32:47]
	s_waitcnt lgkmcnt(2)
	v_mfma_f32_32x32x16_bf16 v[32:47], v[244:247], v[240:243], v[32:47]
	s_waitcnt lgkmcnt(0)
	v_mfma_f32_32x32x16_bf16 v[32:47], v[252:255], v[248:251], v[32:47]
	s_nop 11
	v_add_f32_e32 v16, v16, v32
	v_add_f32_e32 v17, v17, v33
	v_add_f32_e32 v18, v18, v34
	v_add_f32_e32 v19, v19, v35
	v_add_f32_e32 v20, v20, v36
	v_add_f32_e32 v21, v21, v37
	v_add_f32_e32 v22, v22, v38
	v_add_f32_e32 v23, v23, v39
	v_add_f32_e32 v24, v24, v40
	v_add_f32_e32 v25, v25, v41
	v_add_f32_e32 v26, v26, v42
	v_add_f32_e32 v27, v27, v43
	v_add_f32_e32 v28, v28, v44
	v_add_f32_e32 v29, v29, v45
	v_add_f32_e32 v30, v30, v46
	v_add_f32_e32 v31, v31, v47
	v_cvt_pk_bf16_f32 v240, v16, v17
	v_cvt_pk_bf16_f32 v241, v18, v19
	v_cvt_pk_bf16_f32 v242, v20, v21
	v_cvt_pk_bf16_f32 v243, v22, v23
	v_cvt_pk_bf16_f32 v244, v24, v25
	v_cvt_pk_bf16_f32 v245, v26, v27
	v_cvt_pk_bf16_f32 v246, v28, v29
	v_cvt_pk_bf16_f32 v247, v30, v31
	v_lshl_add_u64 v[226:227], s[98:99], 0, v[152:153]
	s_nop 0
	v_permlane32_swap_b32_e32 v240, v242
	v_permlane32_swap_b32_e32 v241, v243
	v_permlane32_swap_b32_e32 v244, v246
	v_permlane32_swap_b32_e32 v245, v247
	global_store_dwordx4 v[226:227], v[240:243], off
	global_store_dwordx4 v[226:227], v[244:247], off offset:32

.Lsw4_join:
	ds_write_b16 v144, v136 offset:62464
	ds_write_b16_d16_hi v144, v136 offset:62608
	ds_write_b16 v144, v137 offset:62752
	ds_write_b16_d16_hi v144, v137 offset:62896
	ds_write_b16 v144, v138 offset:63040
	ds_write_b16_d16_hi v144, v138 offset:63184
	ds_write_b16 v144, v139 offset:63328
	ds_write_b16_d16_hi v144, v139 offset:63472
	s_and_saveexec_b64 s[52:53], s[0:1]
	ds_write_b32 v205, v201
	s_or_b64 exec, exec, s[52:53]
	s_waitcnt lgkmcnt(0)
	s_barrier
	s_and_saveexec_b64 s[52:53], s[4:5]
	s_cbranch_execz .LBB0_886
	s_add_i32 s10, s79, 0xfffffec0
	s_add_i32 s81, s80, 0x140
	s_and_b64 s[84:85], s[48:49], exec
	s_cselect_b32 s10, s10, s81
	s_add_u32 s84, s46, s10
	s_addc_u32 s85, 0, s47
	s_lshl_b64 s[98:99], s[84:85], 11
	ds_read_b128 v[214:217], v209 offset:53248
	ds_read_b128 v[218:221], v210 offset:62464
	ds_read_b128 v[222:225], v209 offset:53280
	ds_read_b128 v[226:229], v210 offset:62496
	ds_read_b128 v[240:243], v209 offset:53312
	ds_read_b128 v[244:247], v210 offset:62528
	ds_read_b128 v[248:251], v209 offset:53344
	ds_read_b128 v[252:255], v210 offset:62560
	s_waitcnt lgkmcnt(6)
	v_mfma_f32_32x32x16_bf16 v[16:31], v[218:221], v[214:217], 0
	ds_read_b128 v[214:217], v206 offset:17408
	ds_read_b128 v[218:221], v207
	s_waitcnt lgkmcnt(6)
	v_mfma_f32_32x32x16_bf16 v[16:31], v[226:229], v[222:225], v[16:31]
	ds_read_b128 v[222:225], v206 offset:17440
	ds_read_b128 v[226:229], v207 offset:32
	s_waitcnt lgkmcnt(6)
	v_mfma_f32_32x32x16_bf16 v[16:31], v[244:247], v[240:243], v[16:31]
	ds_read_b128 v[240:243], v206 offset:17472
	ds_read_b128 v[244:247], v207 offset:64
	s_waitcnt lgkmcnt(6)
	v_mfma_f32_32x32x16_bf16 v[16:31], v[252:255], v[248:251], v[16:31]
	ds_read_b128 v[248:251], v206 offset:17504
	ds_read_b128 v[252:255], v207 offset:96
	s_waitcnt lgkmcnt(6)
	v_mfma_f32_32x32x16_bf16 v[32:47], v[218:221], v[214:217], 0
	ds_read_b128 v[214:217], v206 offset:17536
	ds_read_b128 v[218:221], v207 offset:128
	s_waitcnt lgkmcnt(6)
	v_mfma_f32_32x32x16_bf16 v[32:47], v[226:229], v[222:225], v[32:47]
	ds_read_b128 v[222:225], v206 offset:17568
	ds_read_b128 v[226:229], v207 offset:160
	s_waitcnt lgkmcnt(6)
	v_mfma_f32_32x32x16_bf16 v[32:47], v[244:247], v[240:243], v[32:47]
	ds_read_b128 v[240:243], v206 offset:17600
	ds_read_b128 v[244:247], v207 offset:192
	s_waitcnt lgkmcnt(6)
	v_mfma_f32_32x32x16_bf16 v[32:47], v[252:255], v[248:251], v[32:47]
	ds_read_b128 v[248:251], v206 offset:17632
	ds_read_b128 v[252:255], v207 offset:224
	s_waitcnt lgkmcnt(6)
	v_mfma_f32_32x32x16_bf16 v[32:47], v[218:221], v[214:217], v[32:47]
	s_waitcnt lgkmcnt(4)
	v_mfma_f32_32x32x16_bf16 v[32:47], v[226:229], v[222:225], v[32:47]
	s_waitcnt lgkmcnt(2)
	v_mfma_f32_32x32x16_bf16 v[32:47], v[244:247], v[240:243], v[32:47]
	s_waitcnt lgkmcnt(0)
	v_mfma_f32_32x32x16_bf16 v[32:47], v[252:255], v[248:251], v[32:47]
	s_nop 11
	v_add_f32_e32 v16, v16, v32
	v_add_f32_e32 v17, v17, v33
	v_add_f32_e32 v18, v18, v34
	v_add_f32_e32 v19, v19, v35
	v_add_f32_e32 v20, v20, v36
	v_add_f32_e32 v21, v21, v37
	v_add_f32_e32 v22, v22, v38
	v_add_f32_e32 v23, v23, v39
	v_add_f32_e32 v24, v24, v40
	v_add_f32_e32 v25, v25, v41
	v_add_f32_e32 v26, v26, v42
	v_add_f32_e32 v27, v27, v43
	v_add_f32_e32 v28, v28, v44
	v_add_f32_e32 v29, v29, v45
	v_add_f32_e32 v30, v30, v46
	v_add_f32_e32 v31, v31, v47
	v_cvt_pk_bf16_f32 v240, v16, v17
	v_cvt_pk_bf16_f32 v241, v18, v19
	v_cvt_pk_bf16_f32 v242, v20, v21
	v_cvt_pk_bf16_f32 v243, v22, v23
	v_cvt_pk_bf16_f32 v244, v24, v25
	v_cvt_pk_bf16_f32 v245, v26, v27
	v_cvt_pk_bf16_f32 v246, v28, v29
	v_cvt_pk_bf16_f32 v247, v30, v31
	v_lshl_add_u64 v[226:227], s[98:99], 0, v[152:153]
	s_nop 0
	v_permlane32_swap_b32_e32 v240, v242
	v_permlane32_swap_b32_e32 v241, v243
	v_permlane32_swap_b32_e32 v244, v246
	v_permlane32_swap_b32_e32 v245, v247
	global_store_dwordx4 v[226:227], v[240:243], off
	global_store_dwordx4 v[226:227], v[244:247], off offset:32

.Lsw5_join:
	ds_write_b16 v144, v140 offset:62464
	ds_write_b16_d16_hi v144, v140 offset:62608
	ds_write_b16 v144, v141 offset:62752
	ds_write_b16_d16_hi v144, v141 offset:62896
	ds_write_b16 v144, v142 offset:63040
	ds_write_b16_d16_hi v144, v142 offset:63184
	ds_write_b16 v144, v143 offset:63328
	ds_write_b16_d16_hi v144, v143 offset:63472
	s_and_saveexec_b64 s[52:53], s[0:1]
	ds_write_b32 v205, v200
	s_or_b64 exec, exec, s[52:53]
	s_waitcnt lgkmcnt(0)
	s_barrier
	s_and_saveexec_b64 s[52:53], s[4:5]
	s_cbranch_execz .LBB0_894
	s_add_i32 s10, s79, 0xffffff00
	s_add_i32 s81, s80, 0x100
	s_and_b64 s[84:85], s[48:49], exec
	s_cselect_b32 s10, s10, s81
	s_add_u32 s84, s46, s10
	s_addc_u32 s85, 0, s47
	s_lshl_b64 s[98:99], s[84:85], 11
	ds_read_b128 v[214:217], v209 offset:53248
	ds_read_b128 v[218:221], v210 offset:62464
	ds_read_b128 v[222:225], v209 offset:53280
	ds_read_b128 v[226:229], v210 offset:62496
	ds_read_b128 v[240:243], v209 offset:53312
	ds_read_b128 v[244:247], v210 offset:62528
	ds_read_b128 v[248:251], v209 offset:53344
	ds_read_b128 v[252:255], v210 offset:62560
	s_waitcnt lgkmcnt(6)
	v_mfma_f32_32x32x16_bf16 v[16:31], v[218:221], v[214:217], 0
	ds_read_b128 v[214:217], v206 offset:17408
	ds_read_b128 v[218:221], v207
	s_waitcnt lgkmcnt(6)
	v_mfma_f32_32x32x16_bf16 v[16:31], v[226:229], v[222:225], v[16:31]
	ds_read_b128 v[222:225], v206 offset:17440
	ds_read_b128 v[226:229], v207 offset:32
	s_waitcnt lgkmcnt(6)
	v_mfma_f32_32x32x16_bf16 v[16:31], v[244:247], v[240:243], v[16:31]
	ds_read_b128 v[240:243], v206 offset:17472
	ds_read_b128 v[244:247], v207 offset:64
	s_waitcnt lgkmcnt(6)
	v_mfma_f32_32x32x16_bf16 v[16:31], v[252:255], v[248:251], v[16:31]
	ds_read_b128 v[248:251], v206 offset:17504
	ds_read_b128 v[252:255], v207 offset:96
	s_waitcnt lgkmcnt(6)
	v_mfma_f32_32x32x16_bf16 v[32:47], v[218:221], v[214:217], 0
	ds_read_b128 v[214:217], v206 offset:17536
	ds_read_b128 v[218:221], v207 offset:128
	s_waitcnt lgkmcnt(6)
	v_mfma_f32_32x32x16_bf16 v[32:47], v[226:229], v[222:225], v[32:47]
	ds_read_b128 v[222:225], v206 offset:17568
	ds_read_b128 v[226:229], v207 offset:160
	s_waitcnt lgkmcnt(6)
	v_mfma_f32_32x32x16_bf16 v[32:47], v[244:247], v[240:243], v[32:47]
	ds_read_b128 v[240:243], v206 offset:17600
	ds_read_b128 v[244:247], v207 offset:192
	s_waitcnt lgkmcnt(6)
	v_mfma_f32_32x32x16_bf16 v[32:47], v[252:255], v[248:251], v[32:47]
	ds_read_b128 v[248:251], v206 offset:17632
	ds_read_b128 v[252:255], v207 offset:224
	s_waitcnt lgkmcnt(6)
	v_mfma_f32_32x32x16_bf16 v[32:47], v[218:221], v[214:217], v[32:47]
	s_waitcnt lgkmcnt(4)
	v_mfma_f32_32x32x16_bf16 v[32:47], v[226:229], v[222:225], v[32:47]
	s_waitcnt lgkmcnt(2)
	v_mfma_f32_32x32x16_bf16 v[32:47], v[244:247], v[240:243], v[32:47]
	s_waitcnt lgkmcnt(0)
	v_mfma_f32_32x32x16_bf16 v[32:47], v[252:255], v[248:251], v[32:47]
	s_nop 11
	v_add_f32_e32 v16, v16, v32
	v_add_f32_e32 v17, v17, v33
	v_add_f32_e32 v18, v18, v34
	v_add_f32_e32 v19, v19, v35
	v_add_f32_e32 v20, v20, v36
	v_add_f32_e32 v21, v21, v37
	v_add_f32_e32 v22, v22, v38
	v_add_f32_e32 v23, v23, v39
	v_add_f32_e32 v24, v24, v40
	v_add_f32_e32 v25, v25, v41
	v_add_f32_e32 v26, v26, v42
	v_add_f32_e32 v27, v27, v43
	v_add_f32_e32 v28, v28, v44
	v_add_f32_e32 v29, v29, v45
	v_add_f32_e32 v30, v30, v46
	v_add_f32_e32 v31, v31, v47
	v_cvt_pk_bf16_f32 v240, v16, v17
	v_cvt_pk_bf16_f32 v241, v18, v19
	v_cvt_pk_bf16_f32 v242, v20, v21
	v_cvt_pk_bf16_f32 v243, v22, v23
	v_cvt_pk_bf16_f32 v244, v24, v25
	v_cvt_pk_bf16_f32 v245, v26, v27
	v_cvt_pk_bf16_f32 v246, v28, v29
	v_cvt_pk_bf16_f32 v247, v30, v31
	v_lshl_add_u64 v[226:227], s[98:99], 0, v[152:153]
	s_nop 0
	v_permlane32_swap_b32_e32 v240, v242
	v_permlane32_swap_b32_e32 v241, v243
	v_permlane32_swap_b32_e32 v244, v246
	v_permlane32_swap_b32_e32 v245, v247
	global_store_dwordx4 v[226:227], v[240:243], off
	global_store_dwordx4 v[226:227], v[244:247], off offset:32
